# gemm1 k-step: first fragment reads of each half issued before the global-load block (as in the other GEMMs)
# baseline (speedup 1.0000x reference)
.LBB0_176:
	s_add_i32 s20, s71, 2
	s_cmp_lt_i32 s20, s90
	s_cselect_b64 s[82:83], -1, 0
	s_cmp_ge_i32 s20, s90
	s_cselect_b64 s[80:81], -1, 0
	s_and_b64 vcc, exec, s[80:81]
	v_add_u32_e32 v157, v137, v139
	ds_read_b128 v[198:201], v157
	v_add_u32_e32 v165, v137, v141
	ds_read_b128 v[202:205], v165 offset:16384
	ds_read_b128 v[206:209], v165 offset:20480
	s_cbranch_vccnz .LBB0_180
	s_add_i32 s74, s15, 0x800
	s_cmp_lt_u32 s71, 14
	s_cselect_b64 s[84:85], -1, 0
	s_and_b64 vcc, s[84:85], exec
	s_cselect_b32 vcc_lo, s74, s15
	v_mov_b32_e32 v81, v80
	s_ashr_i32 vcc_hi, vcc_lo, 31
	v_mov_b32_e32 v82, v80
	v_mov_b32_e32 v83, v80
	s_waitcnt vmcnt(8)
	v_mov_b64_e32 v[64:65], v[80:81]
	v_lshl_add_u64 v[120:121], vcc, 1, v[178:179]
	s_or_b64 vcc, s[84:85], s[4:5]
	v_mov_b64_e32 v[66:67], v[82:83]
	s_and_saveexec_b64 s[84:85], vcc
	s_cbranch_execz .LBB0_179
	global_load_dwordx4 v[64:67], v[120:121], off

.Lm1w_w1:
	ds_write_b128 v135, v[68:71] offset:32768
	v_add_u32_e32 v159, v143, v139
	v_add_u32_e32 v167, v143, v141
	v_add_u32_e32 v161, v153, v139
	v_add_u32_e32 v169, v153, v141
	v_add_u32_e32 v163, v155, v139
	s_waitcnt lgkmcnt(1)
	v_mfma_f32_32x32x16_bf16 v[48:63], v[198:201], v[202:205], v[48:63]
	v_add_u32_e32 v171, v155, v141
	s_add_i32 s21, s71, 3
	s_cmp_ge_i32 s21, s90
	v_mfma_f32_32x32x16_bf16 v[32:47], v[198:201], v[206:209], v[32:47]
	ds_read_b128 v[198:201], v157 offset:4096
	ds_write_b128 v135, v[72:75] offset:49152
	s_waitcnt lgkmcnt(1)
	v_mfma_f32_32x32x16_bf16 v[16:31], v[198:201], v[202:205], v[16:31]
	ds_read_b128 v[202:205], v167 offset:16384
	v_mfma_f32_32x32x16_bf16 v[0:15], v[198:201], v[206:209], v[0:15]
	ds_read_b128 v[198:201], v159
	ds_read_b128 v[206:209], v167 offset:20480
	ds_write_b128 v135, v[92:95] offset:36864
	s_waitcnt lgkmcnt(1)
	v_mfma_f32_32x32x16_bf16 v[48:63], v[198:201], v[202:205], v[48:63]
	v_mfma_f32_32x32x16_bf16 v[32:47], v[198:201], v[206:209], v[32:47]
	ds_read_b128 v[198:201], v159 offset:4096
	ds_write_b128 v135, v[84:87] offset:53248
	s_waitcnt lgkmcnt(1)
	v_mfma_f32_32x32x16_bf16 v[16:31], v[198:201], v[202:205], v[16:31]
	ds_read_b128 v[202:205], v169 offset:16384
	v_mfma_f32_32x32x16_bf16 v[0:15], v[198:201], v[206:209], v[0:15]
	ds_read_b128 v[198:201], v161
	ds_read_b128 v[206:209], v169 offset:20480
	ds_write_b128 v135, v[108:111] offset:40960
	s_waitcnt lgkmcnt(1)
	v_mfma_f32_32x32x16_bf16 v[48:63], v[198:201], v[202:205], v[48:63]
	v_mfma_f32_32x32x16_bf16 v[32:47], v[198:201], v[206:209], v[32:47]
	ds_read_b128 v[198:201], v161 offset:4096
	ds_write_b128 v135, v[100:103] offset:57344
	s_waitcnt lgkmcnt(1)
	v_mfma_f32_32x32x16_bf16 v[16:31], v[198:201], v[202:205], v[16:31]
	ds_read_b128 v[202:205], v171 offset:16384
	v_mfma_f32_32x32x16_bf16 v[0:15], v[198:201], v[206:209], v[0:15]
	ds_read_b128 v[198:201], v163
	ds_read_b128 v[206:209], v171 offset:20480
	ds_write_b128 v135, v[124:127] offset:45056
	s_waitcnt lgkmcnt(1)
	v_mfma_f32_32x32x16_bf16 v[48:63], v[198:201], v[202:205], v[48:63]
	v_mfma_f32_32x32x16_bf16 v[32:47], v[198:201], v[206:209], v[32:47]
	ds_read_b128 v[198:201], v163 offset:4096
	ds_write_b128 v135, v[116:119] offset:61440
	s_waitcnt lgkmcnt(1)
	v_mfma_f32_32x32x16_bf16 v[16:31], v[198:201], v[202:205], v[16:31]
	v_mfma_f32_32x32x16_bf16 v[0:15], v[198:201], v[206:209], v[0:15]
	s_waitcnt lgkmcnt(0)
	s_barrier
	ds_read_b128 v[198:201], v157 offset:32768
	ds_read_b128 v[202:205], v165 offset:49152
	ds_read_b128 v[206:209], v165 offset:53248
	s_cbranch_scc1 .LBB0_184
	s_add_i32 s21, s15, 64
	s_add_i32 s74, s15, 0x840
	s_cmp_lt_u32 s71, 13
	s_cselect_b64 s[84:85], -1, 0
	s_and_b64 vcc, s[84:85], exec
	s_cselect_b32 vcc_lo, s74, s21
	v_mov_b32_e32 v81, v80
	s_ashr_i32 vcc_hi, vcc_lo, 31
	v_mov_b32_e32 v82, v80
	v_mov_b32_e32 v83, v80
	v_mov_b64_e32 v[68:69], v[80:81]
	v_lshl_add_u64 v[116:117], vcc, 1, v[178:179]
	s_or_b64 vcc, s[84:85], s[4:5]
	v_mov_b64_e32 v[70:71], v[82:83]
	s_and_saveexec_b64 s[84:85], vcc
	s_cbranch_execz .LBB0_183
	global_load_dwordx4 v[68:71], v[116:117], off

.LBB0_184:
	s_waitcnt vmcnt(8)
	ds_write_b128 v135, v[64:67]
	s_andn2_b64 vcc, exec, s[82:83]
	s_waitcnt lgkmcnt(1)
	v_mfma_f32_32x32x16_bf16 v[48:63], v[198:201], v[202:205], v[48:63]
	v_mfma_f32_32x32x16_bf16 v[32:47], v[198:201], v[206:209], v[32:47]
	ds_read_b128 v[198:201], v157 offset:36864
	ds_write_b128 v135, v[76:79] offset:16384
	s_waitcnt lgkmcnt(1)
	v_mfma_f32_32x32x16_bf16 v[16:31], v[198:201], v[202:205], v[16:31]
	v_mfma_f32_32x32x16_bf16 v[0:15], v[198:201], v[206:209], v[0:15]
	ds_read_b128 v[198:201], v159 offset:32768
	ds_read_b128 v[202:205], v167 offset:49152
	ds_read_b128 v[206:209], v167 offset:53248
	ds_write_b128 v135, v[96:99] offset:4096
	s_waitcnt lgkmcnt(1)
	v_mfma_f32_32x32x16_bf16 v[48:63], v[198:201], v[202:205], v[48:63]
	v_mfma_f32_32x32x16_bf16 v[32:47], v[198:201], v[206:209], v[32:47]
	ds_read_b128 v[198:201], v159 offset:36864
	ds_write_b128 v135, v[88:91] offset:20480
	s_waitcnt lgkmcnt(1)
	v_mfma_f32_32x32x16_bf16 v[16:31], v[198:201], v[202:205], v[16:31]
	v_mfma_f32_32x32x16_bf16 v[0:15], v[198:201], v[206:209], v[0:15]
	ds_read_b128 v[198:201], v161 offset:32768
	ds_read_b128 v[202:205], v169 offset:49152
	ds_read_b128 v[206:209], v169 offset:53248
	ds_write_b128 v135, v[112:115] offset:8192
	s_waitcnt lgkmcnt(1)
	v_mfma_f32_32x32x16_bf16 v[48:63], v[198:201], v[202:205], v[48:63]
	v_mfma_f32_32x32x16_bf16 v[32:47], v[198:201], v[206:209], v[32:47]
	ds_read_b128 v[198:201], v161 offset:36864
	ds_write_b128 v135, v[104:107] offset:24576
	s_waitcnt lgkmcnt(1)
	v_mfma_f32_32x32x16_bf16 v[16:31], v[198:201], v[202:205], v[16:31]
	v_mfma_f32_32x32x16_bf16 v[0:15], v[198:201], v[206:209], v[0:15]
	ds_read_b128 v[198:201], v163 offset:32768
	ds_read_b128 v[202:205], v171 offset:49152
	ds_read_b128 v[206:209], v171 offset:53248
	ds_write_b128 v135, v[128:131] offset:12288
	s_waitcnt lgkmcnt(1)
	v_mfma_f32_32x32x16_bf16 v[48:63], v[198:201], v[202:205], v[48:63]
	v_mfma_f32_32x32x16_bf16 v[32:47], v[198:201], v[206:209], v[32:47]
	ds_read_b128 v[198:201], v163 offset:36864
	ds_write_b128 v135, v[120:123] offset:28672
	s_waitcnt lgkmcnt(1)
	v_mfma_f32_32x32x16_bf16 v[16:31], v[198:201], v[202:205], v[16:31]
	v_mfma_f32_32x32x16_bf16 v[0:15], v[198:201], v[206:209], v[0:15]
